# attention group loop: loop-edge edit, group parameters selected with s_cselect instead of the scalar branch ladder, on top of the unroll-by-two without K-V copies
# baseline (speedup 1.0000x reference)
.LBB0_621:
	s_add_i32 s20, s16, 11
	s_add_i32 s17, s18, 1
	s_add_i32 s19, s18, -12
	s_add_i32 s100, s16, -7
	s_cmp_gt_u32 s20, 17
	s_cselect_b32 s12, 4, 2
	s_cselect_b32 s19, s100, s19
	s_cmp_lt_u32 s20, 12
	s_cselect_b32 s12, 0, s12
	s_cselect_b32 s19, s18, s19
	s_sub_i32 s21, s18, 17
	s_cmp_lt_u32 s20, 17
	s_cselect_b32 s13, 2, 4
	s_cselect_b32 s21, s16, s21
	s_cmp_lt_u32 s20, 11
	s_cselect_b32 s13, 0, s13
	s_cselect_b32 s21, s17, s21
